# phase 2: the 512 sample rows of the branch-A conv spread over all workgroups (2 rows each, threads 0-127, loads requested before the compiled conv loop) instead of a third pass on workgroups 0-15
# baseline (speedup 1.0000x reference)
.LBB0_354:
	s_cmp_gt_i32 s84, 2
	s_cselect_b64 s[4:5], -1, 0
	s_cmp_lt_i32 s85, 3
	s_cselect_b64 s[6:7], -1, 0
	s_or_b64 s[4:5], s[4:5], s[6:7]
	s_and_b64 vcc, exec, s[4:5]
	s_cbranch_vccnz .LBB0_820
	v_mov_b32_e32 v0, v170
	s_movk_i32 s3, 0x840
	v_ashrrev_i32_e32 v24, 7, v0
	v_lshl_add_u32 v121, s2, 2, v24
	v_cmp_gt_i32_e32 vcc, s3, v121
	s_and_saveexec_b64 s[4:5], vcc
	s_cbranch_execz .LBB0_414
	s_waitcnt lgkmcnt(0)
	s_load_dwordx2 s[10:11], s[0:1], 0x30
	s_load_dwordx2 s[6:7], s[0:1], 0x80
	v_lshlrev_b32_e32 v0, 3, v0
	v_and_b32_e32 v120, 0x3f8, v0
	v_mov_b32_e32 v123, 0
	v_lshlrev_b32_e32 v122, 2, v120
	s_waitcnt lgkmcnt(0)
	v_lshl_add_u64 v[8:9], s[10:11], 0, v[122:123]
	s_movk_i32 s3, 0x2000
	v_add_co_u32_e32 v30, vcc, s3, v8
	s_mov_b64 s[8:9], 0x1000
	s_mov_b64 s[12:13], 0x2000
	v_addc_co_u32_e32 v31, vcc, 0, v9, vcc
	s_waitcnt vmcnt(0)
	v_lshl_add_u64 v[26:27], v[8:9], 0, s[8:9]
	v_lshl_add_u64 v[28:29], v[8:9], 0, s[12:13]
	global_load_dwordx4 v[0:3], v122, s[10:11] offset:16
	global_load_dwordx4 v[4:7], v122, s[10:11]
	global_load_dwordx4 v[8:11], v[30:31], off offset:-4096
	global_load_dwordx4 v[12:15], v[30:31], off
	global_load_dwordx4 v[16:19], v[26:27], off offset:16
	global_load_dwordx4 v[20:23], v[28:29], off offset:16
	s_load_dwordx2 s[10:11], s[0:1], 0xf8
	s_load_dwordx2 s[12:13], s[0:1], 0x10
	s_load_dwordx2 s[14:15], s[0:1], 0x98
	s_lshl_b32 s3, s30, 2
	v_lshlrev_b32_e32 v26, 1, v120
	v_mov_b32_e32 v27, v123
	s_waitcnt lgkmcnt(0)
	v_lshl_add_u64 v[124:125], s[10:11], 0, v[26:27]
	s_add_u32 s10, s6, 0x4658000
	s_addc_u32 s11, s7, 0
	v_lshl_add_u64 v[128:129], s[12:13], 0, v[122:123]
	s_add_u32 s12, s6, 0x4200000
	v_lshl_add_u64 v[126:127], s[14:15], 0, v[26:27]
	s_addc_u32 s13, s7, 0
	s_lshl_b32 s14, s2, 5
	v_lshlrev_b32_e32 v24, 3, v24
	v_lshl_add_u64 v[130:131], s[10:11], 0, v[122:123]
	v_add3_u32 v122, s14, v24, -2
	s_lshl_b32 s24, s30, 5
	s_mov_b64 s[14:15], 0
	s_movk_i32 s25, 0x7ff
	s_movk_i32 s26, 0x3fff
	s_movk_i32 s27, 0x7fe
	s_movk_i32 s28, 0x7fd
	s_movk_i32 s29, 0x7ff
	v_readfirstlane_b32 s100, v170
	s_nop 3
	s_cmpk_lt_u32 s100, 0x80
	s_cbranch_scc0 .Lmy_cs_a
	v_and_b32_e32 v228, 0x7f, v170
	v_lshlrev_b32_e32 v229, 5, v228
	v_lshlrev_b32_e32 v228, 4, v228
	s_load_dwordx2 s[98:99], s[0:1], 0x30
	s_waitcnt lgkmcnt(0)
	global_load_dwordx4 v[204:207], v229, s[98:99]
	global_load_dwordx4 v[208:211], v229, s[98:99] offset:16
	s_add_u32 s98, s98, 0x1000
	s_addc_u32 s99, s99, 0
	global_load_dwordx4 v[212:215], v229, s[98:99]
	global_load_dwordx4 v[216:219], v229, s[98:99] offset:16
	s_add_u32 s98, s98, 0x1000
	s_addc_u32 s99, s99, 0
	global_load_dwordx4 v[220:223], v229, s[98:99]
	global_load_dwordx4 v[224:227], v229, s[98:99] offset:16
	s_lshr_b32 s100, s2, 1
	s_and_b32 s101, s2, 1
	s_lshl_b32 s100, s100, 13
	s_add_u32 s100, s100, 0x2000000
	s_cmp_eq_u32 s101, 0
	s_cbranch_scc0 .Lmy_cs_h1
	s_load_dwordx2 s[98:99], s[0:1], 0xf8
	s_waitcnt lgkmcnt(0)
	s_add_u32 s98, s98, s100
	s_addc_u32 s99, s99, 0
	global_load_dwordx4 v[172:175], v228, s[98:99]
	global_load_dwordx4 v[176:179], v228, s[98:99] offset:2048
	s_load_dwordx2 s[98:99], s[0:1], 0x98
	s_waitcnt lgkmcnt(0)
	s_add_u32 s98, s98, s100
	s_addc_u32 s99, s99, 0
	global_load_dwordx4 v[180:183], v228, s[98:99]
	global_load_dwordx4 v[184:187], v228, s[98:99] offset:2048
	s_lshr_b32 s100, s2, 1
	s_lshl_b32 s100, s100, 13
	s_load_dwordx2 s[98:99], s[0:1], 0x10
	s_waitcnt lgkmcnt(0)
	s_add_u32 s98, s98, s100
	s_addc_u32 s99, s99, 0
	global_load_dwordx4 v[188:191], v229, s[98:99]
	global_load_dwordx4 v[192:195], v229, s[98:99] offset:16
	s_add_u32 s98, s98, 0x1000
	s_addc_u32 s99, s99, 0
	global_load_dwordx4 v[196:199], v229, s[98:99]
	global_load_dwordx4 v[200:203], v229, s[98:99] offset:16
	s_branch .Lmy_cs_a
.Lmy_cs_h1:
	s_load_dwordx2 s[98:99], s[0:1], 0xf8
	s_waitcnt lgkmcnt(0)
	s_add_u32 s98, s98, s100
	s_addc_u32 s99, s99, 0
	global_load_dwordx4 v[172:175], v228, s[98:99]
	global_load_dwordx4 v[176:179], v228, s[98:99] offset:2048
	s_add_u32 s98, s98, 0x1000
	s_addc_u32 s99, s99, 0
	global_load_dwordx4 v[180:183], v228, s[98:99]
	global_load_dwordx4 v[184:187], v228, s[98:99] offset:2048
	s_add_u32 s100, s100, 0x1000
	s_load_dwordx2 s[98:99], s[0:1], 0x98
	s_waitcnt lgkmcnt(0)
	s_add_u32 s98, s98, s100
	s_addc_u32 s99, s99, 0
	global_load_dwordx4 v[188:191], v228, s[98:99]
	global_load_dwordx4 v[192:195], v228, s[98:99] offset:2048
.Lmy_cs_a:
	s_branch .LBB0_358
.LBB0_357:
	s_or_b64 exec, exec, s[18:19]
	v_pk_mul_f32 v[32:33], v[16:17], v[32:33]
	v_pk_mul_f32 v[40:41], v[8:9], v[40:41]
	v_pk_fma_f32 v[32:33], v[0:1], v[46:47], v[32:33]
	v_lshlrev_b32_e32 v50, 16, v30
	v_and_b32_e32 v51, 0xffff0000, v30
	v_pk_fma_f32 v[40:41], v[4:5], v[54:55], v[40:41]
	v_pk_fma_f32 v[24:25], v[20:21], v[24:25], v[32:33]
	v_pk_fma_f32 v[36:37], v[12:13], v[36:37], v[40:41]
	v_pk_mul_f32 v[40:41], v[10:11], v[42:43]
	v_pk_mul_f32 v[32:33], v[24:25], v[50:51]
	v_pk_mul_f32 v[24:25], v[18:19], v[34:35]
	v_pk_fma_f32 v[40:41], v[6:7], v[52:53], v[40:41]
	v_pk_fma_f32 v[24:25], v[2:3], v[44:45], v[24:25]
	v_lshlrev_b32_e32 v48, 16, v28
	v_and_b32_e32 v49, 0xffff0000, v28
	v_lshlrev_b32_e32 v28, 16, v29
	v_and_b32_e32 v29, 0xffff0000, v29
	v_lshlrev_b32_e32 v30, 16, v31
	v_and_b32_e32 v31, 0xffff0000, v31
	v_pk_fma_f32 v[38:39], v[14:15], v[38:39], v[40:41]
	v_pk_fma_f32 v[24:25], v[22:23], v[26:27], v[24:25]
	v_add_u32_e32 v121, s3, v121
	v_pk_mul_f32 v[36:37], v[36:37], v[48:49]
	v_pk_mul_f32 v[28:29], v[38:39], v[28:29]
	v_pk_mul_f32 v[30:31], v[24:25], v[30:31]
	v_cmp_lt_i32_e32 vcc, s29, v121
	v_cvt_pk_bf16_f32 v24, v36, v37
	v_cvt_pk_bf16_f32 v25, v28, v29
	v_cvt_pk_bf16_f32 v26, v32, v33
	v_cvt_pk_bf16_f32 v27, v30, v31
	s_or_b64 s[14:15], vcc, s[14:15]
	v_add_u32_e32 v122, s24, v122
	global_store_dwordx4 v[132:133], v[24:27], off
	s_andn2_b64 exec, exec, s[14:15]
	s_cbranch_execz .LBB0_414

.LBB0_414:
	s_or_b64 exec, exec, s[4:5]
	v_readfirstlane_b32 s100, v170
	s_nop 3
	s_cmpk_lt_u32 s100, 0x80
	s_cbranch_scc0 .Lmy_cs_b
	s_lshr_b32 s100, s2, 1
	s_and_b32 s101, s2, 1
	s_lshl_b32 s100, s100, 13
	s_add_u32 s100, s100, 0x2000000
	s_load_dwordx2 s[98:99], s[0:1], 0x98
	s_waitcnt lgkmcnt(0)
	s_add_u32 s98, s98, s100
	s_addc_u32 s99, s99, 0
	s_cmp_eq_u32 s101, 0
	s_cbranch_scc0 .Lmy_cs_c1
	v_mov_b32_e32 v0, v188
	v_mov_b32_e32 v1, v189
	v_mov_b32_e32 v2, v190
	v_mov_b32_e32 v3, v191
	v_mov_b32_e32 v4, v192
	v_mov_b32_e32 v5, v193
	v_mov_b32_e32 v6, v194
	v_mov_b32_e32 v7, v195
	v_mov_b32_e32 v8, v196
	v_mov_b32_e32 v9, v197
	v_mov_b32_e32 v10, v198
	v_mov_b32_e32 v11, v199
	v_mov_b32_e32 v12, v200
	v_mov_b32_e32 v13, v201
	v_mov_b32_e32 v14, v202
	v_mov_b32_e32 v15, v203
	v_lshlrev_b32_e32 v16, 16, v172
	v_and_b32_e32 v17, 0xffff0000, v172
	v_lshlrev_b32_e32 v18, 16, v173
	v_and_b32_e32 v19, 0xffff0000, v173
	v_lshlrev_b32_e32 v20, 16, v174
	v_and_b32_e32 v21, 0xffff0000, v174
	v_lshlrev_b32_e32 v22, 16, v175
	v_and_b32_e32 v23, 0xffff0000, v175
	v_lshlrev_b32_e32 v24, 16, v176
	v_and_b32_e32 v25, 0xffff0000, v176
	v_lshlrev_b32_e32 v26, 16, v177
	v_and_b32_e32 v27, 0xffff0000, v177
	v_lshlrev_b32_e32 v28, 16, v178
	v_and_b32_e32 v29, 0xffff0000, v178
	v_lshlrev_b32_e32 v30, 16, v179
	v_and_b32_e32 v31, 0xffff0000, v179
	v_lshlrev_b32_e32 v32, 16, v180
	v_and_b32_e32 v33, 0xffff0000, v180
	v_lshlrev_b32_e32 v34, 16, v181
	v_and_b32_e32 v35, 0xffff0000, v181
	v_lshlrev_b32_e32 v36, 16, v182
	v_and_b32_e32 v37, 0xffff0000, v182
	v_lshlrev_b32_e32 v38, 16, v183
	v_and_b32_e32 v39, 0xffff0000, v183
	v_pk_mul_f32 v[40:41], v[204:205], v[0:1]
	v_pk_mul_f32 v[42:43], v[206:207], v[2:3]
	v_pk_mul_f32 v[44:45], v[208:209], v[4:5]
	v_pk_mul_f32 v[46:47], v[210:211], v[6:7]
	v_pk_fma_f32 v[40:41], v[212:213], v[8:9], v[40:41]
	v_pk_fma_f32 v[42:43], v[214:215], v[10:11], v[42:43]
	v_pk_fma_f32 v[44:45], v[216:217], v[12:13], v[44:45]
	v_pk_fma_f32 v[46:47], v[218:219], v[14:15], v[46:47]
	v_pk_fma_f32 v[40:41], v[220:221], v[16:17], v[40:41]
	v_pk_fma_f32 v[42:43], v[222:223], v[18:19], v[42:43]
	v_pk_fma_f32 v[44:45], v[224:225], v[20:21], v[44:45]
	v_pk_fma_f32 v[46:47], v[226:227], v[22:23], v[46:47]
	v_pk_mul_f32 v[40:41], v[32:33], v[40:41]
	v_pk_mul_f32 v[42:43], v[34:35], v[42:43]
	v_pk_mul_f32 v[44:45], v[36:37], v[44:45]
	v_pk_mul_f32 v[46:47], v[38:39], v[46:47]
	v_cvt_pk_bf16_f32 v32, v40, v41
	v_cvt_pk_bf16_f32 v33, v42, v43
	v_cvt_pk_bf16_f32 v34, v44, v45
	v_cvt_pk_bf16_f32 v35, v46, v47
	global_store_dwordx4 v228, v[32:35], s[98:99]
	s_nop 1
	v_lshlrev_b32_e32 v48, 16, v184
	v_and_b32_e32 v49, 0xffff0000, v184
	v_lshlrev_b32_e32 v50, 16, v185
	v_and_b32_e32 v51, 0xffff0000, v185
	v_lshlrev_b32_e32 v52, 16, v186
	v_and_b32_e32 v53, 0xffff0000, v186
	v_lshlrev_b32_e32 v54, 16, v187
	v_and_b32_e32 v55, 0xffff0000, v187
	v_pk_mul_f32 v[40:41], v[204:205], v[8:9]
	v_pk_mul_f32 v[42:43], v[206:207], v[10:11]
	v_pk_mul_f32 v[44:45], v[208:209], v[12:13]
	v_pk_mul_f32 v[46:47], v[210:211], v[14:15]
	v_pk_fma_f32 v[40:41], v[212:213], v[16:17], v[40:41]
	v_pk_fma_f32 v[42:43], v[214:215], v[18:19], v[42:43]
	v_pk_fma_f32 v[44:45], v[216:217], v[20:21], v[44:45]
	v_pk_fma_f32 v[46:47], v[218:219], v[22:23], v[46:47]
	v_pk_fma_f32 v[40:41], v[220:221], v[24:25], v[40:41]
	v_pk_fma_f32 v[42:43], v[222:223], v[26:27], v[42:43]
	v_pk_fma_f32 v[44:45], v[224:225], v[28:29], v[44:45]
	v_pk_fma_f32 v[46:47], v[226:227], v[30:31], v[46:47]
	v_pk_mul_f32 v[40:41], v[48:49], v[40:41]
	v_pk_mul_f32 v[42:43], v[50:51], v[42:43]
	v_pk_mul_f32 v[44:45], v[52:53], v[44:45]
	v_pk_mul_f32 v[46:47], v[54:55], v[46:47]
	v_cvt_pk_bf16_f32 v48, v40, v41
	v_cvt_pk_bf16_f32 v49, v42, v43
	v_cvt_pk_bf16_f32 v50, v44, v45
	v_cvt_pk_bf16_f32 v51, v46, v47
	global_store_dwordx4 v228, v[48:51], s[98:99] offset:2048
	s_nop 1
	s_branch .Lmy_cs_b
.Lmy_cs_c1:
	v_lshlrev_b32_e32 v0, 16, v172
	v_and_b32_e32 v1, 0xffff0000, v172
	v_lshlrev_b32_e32 v2, 16, v173
	v_and_b32_e32 v3, 0xffff0000, v173
	v_lshlrev_b32_e32 v4, 16, v174
	v_and_b32_e32 v5, 0xffff0000, v174
	v_lshlrev_b32_e32 v6, 16, v175
	v_and_b32_e32 v7, 0xffff0000, v175
	v_lshlrev_b32_e32 v8, 16, v176
	v_and_b32_e32 v9, 0xffff0000, v176
	v_lshlrev_b32_e32 v10, 16, v177
	v_and_b32_e32 v11, 0xffff0000, v177
	v_lshlrev_b32_e32 v12, 16, v178
	v_and_b32_e32 v13, 0xffff0000, v178
	v_lshlrev_b32_e32 v14, 16, v179
	v_and_b32_e32 v15, 0xffff0000, v179
	v_lshlrev_b32_e32 v16, 16, v180
	v_and_b32_e32 v17, 0xffff0000, v180
	v_lshlrev_b32_e32 v18, 16, v181
	v_and_b32_e32 v19, 0xffff0000, v181
	v_lshlrev_b32_e32 v20, 16, v182
	v_and_b32_e32 v21, 0xffff0000, v182
	v_lshlrev_b32_e32 v22, 16, v183
	v_and_b32_e32 v23, 0xffff0000, v183
	v_lshlrev_b32_e32 v24, 16, v184
	v_and_b32_e32 v25, 0xffff0000, v184
	v_lshlrev_b32_e32 v26, 16, v185
	v_and_b32_e32 v27, 0xffff0000, v185
	v_lshlrev_b32_e32 v28, 16, v186
	v_and_b32_e32 v29, 0xffff0000, v186
	v_lshlrev_b32_e32 v30, 16, v187
	v_and_b32_e32 v31, 0xffff0000, v187
	s_add_u32 s98, s98, 0x1000
	s_addc_u32 s99, s99, 0
	v_lshlrev_b32_e32 v32, 16, v188
	v_and_b32_e32 v33, 0xffff0000, v188
	v_lshlrev_b32_e32 v34, 16, v189
	v_and_b32_e32 v35, 0xffff0000, v189
	v_lshlrev_b32_e32 v36, 16, v190
	v_and_b32_e32 v37, 0xffff0000, v190
	v_lshlrev_b32_e32 v38, 16, v191
	v_and_b32_e32 v39, 0xffff0000, v191
	v_pk_mul_f32 v[40:41], v[204:205], v[0:1]
	v_pk_mul_f32 v[42:43], v[206:207], v[2:3]
	v_pk_mul_f32 v[44:45], v[208:209], v[4:5]
	v_pk_mul_f32 v[46:47], v[210:211], v[6:7]
	v_pk_fma_f32 v[40:41], v[212:213], v[8:9], v[40:41]
	v_pk_fma_f32 v[42:43], v[214:215], v[10:11], v[42:43]
	v_pk_fma_f32 v[44:45], v[216:217], v[12:13], v[44:45]
	v_pk_fma_f32 v[46:47], v[218:219], v[14:15], v[46:47]
	v_pk_fma_f32 v[40:41], v[220:221], v[16:17], v[40:41]
	v_pk_fma_f32 v[42:43], v[222:223], v[18:19], v[42:43]
	v_pk_fma_f32 v[44:45], v[224:225], v[20:21], v[44:45]
	v_pk_fma_f32 v[46:47], v[226:227], v[22:23], v[46:47]
	v_pk_mul_f32 v[40:41], v[32:33], v[40:41]
	v_pk_mul_f32 v[42:43], v[34:35], v[42:43]
	v_pk_mul_f32 v[44:45], v[36:37], v[44:45]
	v_pk_mul_f32 v[46:47], v[38:39], v[46:47]
	v_cvt_pk_bf16_f32 v32, v40, v41
	v_cvt_pk_bf16_f32 v33, v42, v43
	v_cvt_pk_bf16_f32 v34, v44, v45
	v_cvt_pk_bf16_f32 v35, v46, v47
	global_store_dwordx4 v228, v[32:35], s[98:99]
	s_nop 1
	v_lshlrev_b32_e32 v48, 16, v192
	v_and_b32_e32 v49, 0xffff0000, v192
	v_lshlrev_b32_e32 v50, 16, v193
	v_and_b32_e32 v51, 0xffff0000, v193
	v_lshlrev_b32_e32 v52, 16, v194
	v_and_b32_e32 v53, 0xffff0000, v194
	v_lshlrev_b32_e32 v54, 16, v195
	v_and_b32_e32 v55, 0xffff0000, v195
	v_pk_mul_f32 v[40:41], v[204:205], v[8:9]
	v_pk_mul_f32 v[42:43], v[206:207], v[10:11]
	v_pk_mul_f32 v[44:45], v[208:209], v[12:13]
	v_pk_mul_f32 v[46:47], v[210:211], v[14:15]
	v_pk_fma_f32 v[40:41], v[212:213], v[16:17], v[40:41]
	v_pk_fma_f32 v[42:43], v[214:215], v[18:19], v[42:43]
	v_pk_fma_f32 v[44:45], v[216:217], v[20:21], v[44:45]
	v_pk_fma_f32 v[46:47], v[218:219], v[22:23], v[46:47]
	v_pk_fma_f32 v[40:41], v[220:221], v[24:25], v[40:41]
	v_pk_fma_f32 v[42:43], v[222:223], v[26:27], v[42:43]
	v_pk_fma_f32 v[44:45], v[224:225], v[28:29], v[44:45]
	v_pk_fma_f32 v[46:47], v[226:227], v[30:31], v[46:47]
	v_pk_mul_f32 v[40:41], v[48:49], v[40:41]
	v_pk_mul_f32 v[42:43], v[50:51], v[42:43]
	v_pk_mul_f32 v[44:45], v[52:53], v[44:45]
	v_pk_mul_f32 v[46:47], v[54:55], v[46:47]
	v_cvt_pk_bf16_f32 v48, v40, v41
	v_cvt_pk_bf16_f32 v49, v42, v43
	v_cvt_pk_bf16_f32 v50, v44, v45
	v_cvt_pk_bf16_f32 v51, v46, v47
	global_store_dwordx4 v228, v[48:51], s[98:99] offset:2048
	s_nop 1
	s_lshr_b32 s100, s2, 1
	s_lshl_b32 s100, s100, 13
	s_add_u32 s100, s100, 0x4658000
	s_load_dwordx2 s[98:99], s[0:1], 0x80
	s_waitcnt lgkmcnt(0)
	s_add_u32 s98, s98, s100
	s_addc_u32 s99, s99, 0
	global_store_dwordx4 v229, v[16:19], s[98:99]
	global_store_dwordx4 v229, v[20:23], s[98:99] offset:16
	s_add_u32 s98, s98, 0x1000
	s_addc_u32 s99, s99, 0
	global_store_dwordx4 v229, v[24:27], s[98:99]
	global_store_dwordx4 v229, v[28:31], s[98:99] offset:16
